# layer-1 memory attention body: cross-lane max/sum by v_permlane16/32_swap (VALU) instead of ds_bpermute round trips; V operand prefetch started before the cross-lane sum
# speedup vs baseline: 1.0040x; 1.0026x over previous
.Lma_nostag:
	v_add_u32_e32 v150, 0x9000, v122
	v_add_u32_e32 v151, 0x9000, v123
	v_add_u32_e32 v152, 0x9000, v124
	v_add_u32_e32 v153, 0x9000, v125
	ds_read_b128 v[200:203], v128
	ds_read_b128 v[204:207], v128 offset:64
	ds_read_b128 v[208:211], v128 offset:2304
	ds_read_b128 v[212:215], v128 offset:2368
	ds_read_b128 v[216:219], v128 offset:4608
	ds_read_b128 v[220:223], v128 offset:4672
	ds_read_b128 v[224:227], v128 offset:6912
	ds_read_b128 v[228:231], v128 offset:6976
	s_waitcnt vmcnt(10)
	s_waitcnt lgkmcnt(4)
	v_mfma_f32_16x16x32_bf16 v[44:47], v[200:203], v[108:111], 0
	v_mfma_f32_16x16x32_bf16 v[48:51], v[208:211], v[108:111], 0
	v_mfma_f32_16x16x32_bf16 v[44:47], v[204:207], v[60:63], v[44:47]
	v_mfma_f32_16x16x32_bf16 v[48:51], v[212:215], v[60:63], v[48:51]
	ds_read_b128 v[200:203], v128 offset:9216
	ds_read_b128 v[204:207], v128 offset:9280
	ds_read_b128 v[208:211], v128 offset:11520
	ds_read_b128 v[212:215], v128 offset:11584
	s_waitcnt lgkmcnt(4)
	v_mfma_f32_16x16x32_bf16 v[52:55], v[216:219], v[108:111], 0
	v_mfma_f32_16x16x32_bf16 v[56:59], v[224:227], v[108:111], 0
	v_mfma_f32_16x16x32_bf16 v[52:55], v[220:223], v[60:63], v[52:55]
	v_mfma_f32_16x16x32_bf16 v[56:59], v[228:231], v[60:63], v[56:59]
	ds_read_b128 v[216:219], v128 offset:13824
	ds_read_b128 v[220:223], v128 offset:13888
	ds_read_b128 v[224:227], v128 offset:16128
	ds_read_b128 v[228:231], v128 offset:16192
	s_waitcnt lgkmcnt(4)
	v_mfma_f32_16x16x32_bf16 v[64:67], v[200:203], v[108:111], 0
	v_mfma_f32_16x16x32_bf16 v[68:71], v[208:211], v[108:111], 0
	v_mfma_f32_16x16x32_bf16 v[64:67], v[204:207], v[60:63], v[64:67]
	v_mfma_f32_16x16x32_bf16 v[68:71], v[212:215], v[60:63], v[68:71]
	ds_read_b128 v[200:203], v128 offset:18432
	ds_read_b128 v[204:207], v128 offset:18496
	ds_read_b128 v[208:211], v128 offset:20736
	ds_read_b128 v[212:215], v128 offset:20800
	s_waitcnt lgkmcnt(4)
	v_mfma_f32_16x16x32_bf16 v[72:75], v[216:219], v[108:111], 0
	v_mfma_f32_16x16x32_bf16 v[76:79], v[224:227], v[108:111], 0
	v_mfma_f32_16x16x32_bf16 v[72:75], v[220:223], v[60:63], v[72:75]
	v_mfma_f32_16x16x32_bf16 v[76:79], v[228:231], v[60:63], v[76:79]
	ds_read_b128 v[216:219], v128 offset:23040
	ds_read_b128 v[220:223], v128 offset:23104
	ds_read_b128 v[224:227], v128 offset:25344
	ds_read_b128 v[228:231], v128 offset:25408
	s_waitcnt lgkmcnt(4)
	v_mfma_f32_16x16x32_bf16 v[80:83], v[200:203], v[108:111], 0
	v_mfma_f32_16x16x32_bf16 v[84:87], v[208:211], v[108:111], 0
	v_mfma_f32_16x16x32_bf16 v[80:83], v[204:207], v[60:63], v[80:83]
	v_mfma_f32_16x16x32_bf16 v[84:87], v[212:215], v[60:63], v[84:87]
	ds_read_b128 v[200:203], v128 offset:27648
	ds_read_b128 v[204:207], v128 offset:27712
	ds_read_b128 v[208:211], v128 offset:29952
	ds_read_b128 v[212:215], v128 offset:30016
	s_waitcnt lgkmcnt(4)
	v_mfma_f32_16x16x32_bf16 v[88:91], v[216:219], v[108:111], 0
	v_mfma_f32_16x16x32_bf16 v[92:95], v[224:227], v[108:111], 0
	v_mfma_f32_16x16x32_bf16 v[88:91], v[220:223], v[60:63], v[88:91]
	v_mfma_f32_16x16x32_bf16 v[92:95], v[228:231], v[60:63], v[92:95]
	ds_read_b128 v[216:219], v128 offset:32256
	ds_read_b128 v[220:223], v128 offset:32320
	ds_read_b128 v[224:227], v128 offset:34560
	ds_read_b128 v[228:231], v128 offset:34624
	s_waitcnt lgkmcnt(4)
	v_mfma_f32_16x16x32_bf16 v[96:99], v[200:203], v[108:111], 0
	v_mfma_f32_16x16x32_bf16 v[100:103], v[208:211], v[108:111], 0
	v_mfma_f32_16x16x32_bf16 v[96:99], v[204:207], v[60:63], v[96:99]
	v_mfma_f32_16x16x32_bf16 v[100:103], v[212:215], v[60:63], v[100:103]
	s_waitcnt lgkmcnt(0)
	v_mfma_f32_16x16x32_bf16 v[104:107], v[216:219], v[108:111], 0
	v_mfma_f32_16x16x32_bf16 v[130:133], v[224:227], v[108:111], 0
	v_mfma_f32_16x16x32_bf16 v[104:107], v[220:223], v[60:63], v[104:107]
	v_mfma_f32_16x16x32_bf16 v[130:133], v[228:231], v[60:63], v[130:133]
	s_nop 7
	v_max3_f32 v154, v44, v45, s13
	v_max3_f32 v154, v46, v47, v154
	v_max3_f32 v154, v48, v49, v154
	v_max3_f32 v154, v50, v51, v154
	v_max3_f32 v154, v52, v53, v154
	v_max3_f32 v154, v54, v55, v154
	v_max3_f32 v154, v56, v57, v154
	v_max3_f32 v154, v58, v59, v154
	v_max3_f32 v154, v64, v65, v154
	v_max3_f32 v154, v66, v67, v154
	v_max3_f32 v154, v68, v69, v154
	v_max3_f32 v154, v70, v71, v154
	v_max3_f32 v154, v72, v73, v154
	v_max3_f32 v154, v74, v75, v154
	v_max3_f32 v154, v76, v77, v154
	v_max3_f32 v154, v78, v79, v154
	v_max3_f32 v154, v80, v81, v154
	v_max3_f32 v154, v82, v83, v154
	v_max3_f32 v154, v84, v85, v154
	v_max3_f32 v154, v86, v87, v154
	v_max3_f32 v154, v88, v89, v154
	v_max3_f32 v154, v90, v91, v154
	v_max3_f32 v154, v92, v93, v154
	v_max3_f32 v154, v94, v95, v154
	v_max3_f32 v154, v96, v97, v154
	v_max3_f32 v154, v98, v99, v154
	v_max3_f32 v154, v100, v101, v154
	v_max3_f32 v154, v102, v103, v154
	v_max3_f32 v154, v104, v105, v154
	v_max3_f32 v154, v106, v107, v154
	v_max3_f32 v154, v130, v131, v154
	v_max3_f32 v154, v132, v133, v154
	v_mov_b32_e32 v155, v154
	s_nop 1
	v_permlane16_swap_b32_e32 v154, v155
	v_max_f32_e32 v154, v154, v155
	v_mov_b32_e32 v155, v154
	s_nop 1
	v_permlane32_swap_b32_e32 v154, v155
	v_max_f32_e32 v154, v154, v155
	v_sub_f32_e32 v44, v44, v154
	v_exp_f32_e32 v44, v44
	v_sub_f32_e32 v45, v45, v154
	v_exp_f32_e32 v45, v45
	v_add_f32_e32 v172, 0, v44
	v_sub_f32_e32 v46, v46, v154
	v_exp_f32_e32 v46, v46
	v_add_f32_e32 v172, v45, v172
	v_sub_f32_e32 v47, v47, v154
	v_exp_f32_e32 v47, v47
	v_add_f32_e32 v172, v46, v172
	v_sub_f32_e32 v48, v48, v154
	v_exp_f32_e32 v48, v48
	v_add_f32_e32 v172, v47, v172
	v_sub_f32_e32 v49, v49, v154
	v_exp_f32_e32 v49, v49
	v_add_f32_e32 v172, v48, v172
	v_sub_f32_e32 v50, v50, v154
	v_exp_f32_e32 v50, v50
	v_add_f32_e32 v172, v49, v172
	v_sub_f32_e32 v51, v51, v154
	v_exp_f32_e32 v51, v51
	v_add_f32_e32 v172, v50, v172
	v_sub_f32_e32 v52, v52, v154
	v_exp_f32_e32 v52, v52
	v_add_f32_e32 v172, v51, v172
	v_sub_f32_e32 v53, v53, v154
	v_exp_f32_e32 v53, v53
	v_add_f32_e32 v172, v52, v172
	v_sub_f32_e32 v54, v54, v154
	v_exp_f32_e32 v54, v54
	v_add_f32_e32 v172, v53, v172
	v_sub_f32_e32 v55, v55, v154
	v_exp_f32_e32 v55, v55
	v_add_f32_e32 v172, v54, v172
	v_sub_f32_e32 v56, v56, v154
	v_exp_f32_e32 v56, v56
	v_add_f32_e32 v172, v55, v172
	v_sub_f32_e32 v57, v57, v154
	v_exp_f32_e32 v57, v57
	v_add_f32_e32 v172, v56, v172
	v_sub_f32_e32 v58, v58, v154
	v_exp_f32_e32 v58, v58
	v_add_f32_e32 v172, v57, v172
	v_sub_f32_e32 v59, v59, v154
	v_exp_f32_e32 v59, v59
	v_add_f32_e32 v172, v58, v172
	v_sub_f32_e32 v64, v64, v154
	v_exp_f32_e32 v64, v64
	v_add_f32_e32 v172, v59, v172
	v_sub_f32_e32 v65, v65, v154
	v_exp_f32_e32 v65, v65
	v_add_f32_e32 v172, v64, v172
	v_sub_f32_e32 v66, v66, v154
	v_exp_f32_e32 v66, v66
	v_add_f32_e32 v172, v65, v172
	v_sub_f32_e32 v67, v67, v154
	v_exp_f32_e32 v67, v67
	v_add_f32_e32 v172, v66, v172
	v_sub_f32_e32 v68, v68, v154
	v_exp_f32_e32 v68, v68
	v_add_f32_e32 v172, v67, v172
	v_sub_f32_e32 v69, v69, v154
	v_exp_f32_e32 v69, v69
	v_add_f32_e32 v172, v68, v172
	v_sub_f32_e32 v70, v70, v154
	v_exp_f32_e32 v70, v70
	v_add_f32_e32 v172, v69, v172
	v_sub_f32_e32 v71, v71, v154
	v_exp_f32_e32 v71, v71
	v_add_f32_e32 v172, v70, v172
	v_sub_f32_e32 v72, v72, v154
	v_exp_f32_e32 v72, v72
	v_add_f32_e32 v172, v71, v172
	v_sub_f32_e32 v73, v73, v154
	v_exp_f32_e32 v73, v73
	v_add_f32_e32 v172, v72, v172
	v_sub_f32_e32 v74, v74, v154
	v_exp_f32_e32 v74, v74
	v_add_f32_e32 v172, v73, v172
	v_sub_f32_e32 v75, v75, v154
	v_exp_f32_e32 v75, v75
	v_add_f32_e32 v172, v74, v172
	v_sub_f32_e32 v76, v76, v154
	v_exp_f32_e32 v76, v76
	v_add_f32_e32 v172, v75, v172
	v_sub_f32_e32 v77, v77, v154
	v_exp_f32_e32 v77, v77
	v_add_f32_e32 v172, v76, v172
	v_sub_f32_e32 v78, v78, v154
	v_exp_f32_e32 v78, v78
	v_add_f32_e32 v172, v77, v172
	v_sub_f32_e32 v79, v79, v154
	v_exp_f32_e32 v79, v79
	v_add_f32_e32 v172, v78, v172
	v_sub_f32_e32 v80, v80, v154
	v_exp_f32_e32 v80, v80
	v_add_f32_e32 v172, v79, v172
	v_sub_f32_e32 v81, v81, v154
	v_exp_f32_e32 v81, v81
	v_add_f32_e32 v172, v80, v172
	v_sub_f32_e32 v82, v82, v154
	v_exp_f32_e32 v82, v82
	v_add_f32_e32 v172, v81, v172
	v_sub_f32_e32 v83, v83, v154
	v_exp_f32_e32 v83, v83
	v_add_f32_e32 v172, v82, v172
	v_sub_f32_e32 v84, v84, v154
	v_exp_f32_e32 v84, v84
	v_add_f32_e32 v172, v83, v172
	v_sub_f32_e32 v85, v85, v154
	v_exp_f32_e32 v85, v85
	v_add_f32_e32 v172, v84, v172
	v_sub_f32_e32 v86, v86, v154
	v_exp_f32_e32 v86, v86
	v_add_f32_e32 v172, v85, v172
	v_sub_f32_e32 v87, v87, v154
	v_exp_f32_e32 v87, v87
	v_add_f32_e32 v172, v86, v172
	v_sub_f32_e32 v88, v88, v154
	v_exp_f32_e32 v88, v88
	v_add_f32_e32 v172, v87, v172
	v_sub_f32_e32 v89, v89, v154
	v_exp_f32_e32 v89, v89
	v_add_f32_e32 v172, v88, v172
	v_sub_f32_e32 v90, v90, v154
	v_exp_f32_e32 v90, v90
	v_add_f32_e32 v172, v89, v172
	v_sub_f32_e32 v91, v91, v154
	v_exp_f32_e32 v91, v91
	v_add_f32_e32 v172, v90, v172
	v_sub_f32_e32 v92, v92, v154
	v_exp_f32_e32 v92, v92
	v_add_f32_e32 v172, v91, v172
	v_sub_f32_e32 v93, v93, v154
	v_exp_f32_e32 v93, v93
	v_add_f32_e32 v172, v92, v172
	v_sub_f32_e32 v94, v94, v154
	v_exp_f32_e32 v94, v94
	v_add_f32_e32 v172, v93, v172
	v_sub_f32_e32 v95, v95, v154
	v_exp_f32_e32 v95, v95
	v_add_f32_e32 v172, v94, v172
	v_sub_f32_e32 v96, v96, v154
	v_exp_f32_e32 v96, v96
	v_add_f32_e32 v172, v95, v172
	v_sub_f32_e32 v97, v97, v154
	v_exp_f32_e32 v97, v97
	v_add_f32_e32 v172, v96, v172
	v_sub_f32_e32 v98, v98, v154
	v_exp_f32_e32 v98, v98
	v_add_f32_e32 v172, v97, v172
	v_sub_f32_e32 v99, v99, v154
	v_exp_f32_e32 v99, v99
	v_add_f32_e32 v172, v98, v172
	v_sub_f32_e32 v100, v100, v154
	v_exp_f32_e32 v100, v100
	v_add_f32_e32 v172, v99, v172
	v_sub_f32_e32 v101, v101, v154
	v_exp_f32_e32 v101, v101
	v_add_f32_e32 v172, v100, v172
	v_sub_f32_e32 v102, v102, v154
	v_exp_f32_e32 v102, v102
	v_add_f32_e32 v172, v101, v172
	v_sub_f32_e32 v103, v103, v154
	v_exp_f32_e32 v103, v103
	v_add_f32_e32 v172, v102, v172
	v_sub_f32_e32 v104, v104, v154
	v_exp_f32_e32 v104, v104
	v_add_f32_e32 v172, v103, v172
	v_sub_f32_e32 v105, v105, v154
	v_exp_f32_e32 v105, v105
	v_add_f32_e32 v172, v104, v172
	v_sub_f32_e32 v106, v106, v154
	v_exp_f32_e32 v106, v106
	v_add_f32_e32 v172, v105, v172
	v_sub_f32_e32 v107, v107, v154
	v_exp_f32_e32 v107, v107
	v_add_f32_e32 v172, v106, v172
	v_sub_f32_e32 v130, v130, v154
	v_exp_f32_e32 v130, v130
	v_add_f32_e32 v172, v107, v172
	v_sub_f32_e32 v131, v131, v154
	v_exp_f32_e32 v131, v131
	v_add_f32_e32 v172, v130, v172
	v_sub_f32_e32 v132, v132, v154
	v_exp_f32_e32 v132, v132
	v_add_f32_e32 v172, v131, v172
	v_sub_f32_e32 v133, v133, v154
	v_exp_f32_e32 v133, v133
	v_add_f32_e32 v172, v132, v172
	s_nop 0
	v_add_f32_e32 v172, v133, v172
	ds_read2_b64 v[200:203], v150 offset0:0 offset1:4
	ds_read2_b64 v[204:207], v151 offset0:0 offset1:4
	ds_read2_b64 v[208:211], v152 offset0:0 offset1:4
	ds_read2_b64 v[212:215], v153 offset0:0 offset1:4
	ds_read2_b64 v[216:219], v150 offset0:8 offset1:12
	ds_read2_b64 v[220:223], v151 offset0:8 offset1:12
	ds_read2_b64 v[224:227], v152 offset0:8 offset1:12
	ds_read2_b64 v[228:231], v153 offset0:8 offset1:12
	v_mov_b32_e32 v155, v172
	s_nop 1
	v_permlane16_swap_b32_e32 v172, v155
	v_add_f32_e32 v172, v172, v155
	v_mov_b32_e32 v155, v172
	s_nop 1
	v_permlane32_swap_b32_e32 v172, v155
	v_add_f32_e32 v172, v172, v155
	v_cvt_pk_bf16_f32 v44, v44, v45
	v_cvt_pk_bf16_f32 v45, v46, v47
	v_cvt_pk_bf16_f32 v46, v48, v49
	v_cvt_pk_bf16_f32 v47, v50, v51
	v_cvt_pk_bf16_f32 v52, v52, v53
	v_cvt_pk_bf16_f32 v53, v54, v55
	v_cvt_pk_bf16_f32 v54, v56, v57
	v_cvt_pk_bf16_f32 v55, v58, v59
	s_waitcnt lgkmcnt(4)
	s_nop 1
	v_mfma_f32_16x16x32_bf16 v[134:137], v[200:203], v[44:47], 0
	v_mfma_f32_16x16x32_bf16 v[138:141], v[204:207], v[44:47], 0
	v_mfma_f32_16x16x32_bf16 v[142:145], v[208:211], v[44:47], 0
	v_mfma_f32_16x16x32_bf16 v[146:149], v[212:215], v[44:47], 0
	ds_read2_b64 v[200:203], v150 offset0:16 offset1:20
	ds_read2_b64 v[204:207], v151 offset0:16 offset1:20
	ds_read2_b64 v[208:211], v152 offset0:16 offset1:20
	ds_read2_b64 v[212:215], v153 offset0:16 offset1:20
	v_cvt_pk_bf16_f32 v64, v64, v65
	v_cvt_pk_bf16_f32 v65, v66, v67
	v_cvt_pk_bf16_f32 v66, v68, v69
	v_cvt_pk_bf16_f32 v67, v70, v71
	s_waitcnt lgkmcnt(4)
	s_nop 1
	v_mfma_f32_16x16x32_bf16 v[134:137], v[216:219], v[52:55], v[134:137]
	v_mfma_f32_16x16x32_bf16 v[138:141], v[220:223], v[52:55], v[138:141]
	v_mfma_f32_16x16x32_bf16 v[142:145], v[224:227], v[52:55], v[142:145]
	v_mfma_f32_16x16x32_bf16 v[146:149], v[228:231], v[52:55], v[146:149]
	ds_read2_b64 v[216:219], v150 offset0:24 offset1:28
	ds_read2_b64 v[220:223], v151 offset0:24 offset1:28
	ds_read2_b64 v[224:227], v152 offset0:24 offset1:28
	ds_read2_b64 v[228:231], v153 offset0:24 offset1:28
	v_cvt_pk_bf16_f32 v72, v72, v73
	v_cvt_pk_bf16_f32 v73, v74, v75
	v_cvt_pk_bf16_f32 v74, v76, v77
	v_cvt_pk_bf16_f32 v75, v78, v79
	s_waitcnt lgkmcnt(4)
	s_nop 1
	v_mfma_f32_16x16x32_bf16 v[134:137], v[200:203], v[64:67], v[134:137]
	v_mfma_f32_16x16x32_bf16 v[138:141], v[204:207], v[64:67], v[138:141]
	v_mfma_f32_16x16x32_bf16 v[142:145], v[208:211], v[64:67], v[142:145]
	v_mfma_f32_16x16x32_bf16 v[146:149], v[212:215], v[64:67], v[146:149]
	ds_read2_b64 v[200:203], v150 offset0:32 offset1:36
	ds_read2_b64 v[204:207], v151 offset0:32 offset1:36
	ds_read2_b64 v[208:211], v152 offset0:32 offset1:36
	ds_read2_b64 v[212:215], v153 offset0:32 offset1:36
	v_cvt_pk_bf16_f32 v80, v80, v81
	v_cvt_pk_bf16_f32 v81, v82, v83
	v_cvt_pk_bf16_f32 v82, v84, v85
	v_cvt_pk_bf16_f32 v83, v86, v87
	s_waitcnt lgkmcnt(4)
	s_nop 1
	v_mfma_f32_16x16x32_bf16 v[134:137], v[216:219], v[72:75], v[134:137]
	v_mfma_f32_16x16x32_bf16 v[138:141], v[220:223], v[72:75], v[138:141]
	v_mfma_f32_16x16x32_bf16 v[142:145], v[224:227], v[72:75], v[142:145]
	v_mfma_f32_16x16x32_bf16 v[146:149], v[228:231], v[72:75], v[146:149]
	ds_read2_b64 v[216:219], v150 offset0:40 offset1:44
	ds_read2_b64 v[220:223], v151 offset0:40 offset1:44
	ds_read2_b64 v[224:227], v152 offset0:40 offset1:44
	ds_read2_b64 v[228:231], v153 offset0:40 offset1:44
	v_cvt_pk_bf16_f32 v88, v88, v89
	v_cvt_pk_bf16_f32 v89, v90, v91
	v_cvt_pk_bf16_f32 v90, v92, v93
	v_cvt_pk_bf16_f32 v91, v94, v95
	s_waitcnt lgkmcnt(4)
	s_nop 1
	v_mfma_f32_16x16x32_bf16 v[134:137], v[200:203], v[80:83], v[134:137]
	v_mfma_f32_16x16x32_bf16 v[138:141], v[204:207], v[80:83], v[138:141]
	v_mfma_f32_16x16x32_bf16 v[142:145], v[208:211], v[80:83], v[142:145]
	v_mfma_f32_16x16x32_bf16 v[146:149], v[212:215], v[80:83], v[146:149]
	ds_read2_b64 v[200:203], v150 offset0:48 offset1:52
	ds_read2_b64 v[204:207], v151 offset0:48 offset1:52
	ds_read2_b64 v[208:211], v152 offset0:48 offset1:52
	ds_read2_b64 v[212:215], v153 offset0:48 offset1:52
	v_cvt_pk_bf16_f32 v96, v96, v97
	v_cvt_pk_bf16_f32 v97, v98, v99
	v_cvt_pk_bf16_f32 v98, v100, v101
	v_cvt_pk_bf16_f32 v99, v102, v103
	s_waitcnt lgkmcnt(4)
	s_nop 1
	v_mfma_f32_16x16x32_bf16 v[134:137], v[216:219], v[88:91], v[134:137]
	v_mfma_f32_16x16x32_bf16 v[138:141], v[220:223], v[88:91], v[138:141]
	v_mfma_f32_16x16x32_bf16 v[142:145], v[224:227], v[88:91], v[142:145]
	v_mfma_f32_16x16x32_bf16 v[146:149], v[228:231], v[88:91], v[146:149]
	ds_read2_b64 v[216:219], v150 offset0:56 offset1:60
	ds_read2_b64 v[220:223], v151 offset0:56 offset1:60
	ds_read2_b64 v[224:227], v152 offset0:56 offset1:60
	ds_read2_b64 v[228:231], v153 offset0:56 offset1:60
	v_cvt_pk_bf16_f32 v104, v104, v105
	v_cvt_pk_bf16_f32 v105, v106, v107
	v_cvt_pk_bf16_f32 v106, v130, v131
	v_cvt_pk_bf16_f32 v107, v132, v133
	s_waitcnt lgkmcnt(4)
	s_nop 1
	v_mfma_f32_16x16x32_bf16 v[134:137], v[200:203], v[96:99], v[134:137]
	v_mfma_f32_16x16x32_bf16 v[138:141], v[204:207], v[96:99], v[138:141]
	v_mfma_f32_16x16x32_bf16 v[142:145], v[208:211], v[96:99], v[142:145]
	v_mfma_f32_16x16x32_bf16 v[146:149], v[212:215], v[96:99], v[146:149]
	s_waitcnt lgkmcnt(0)
	s_nop 1
	v_mfma_f32_16x16x32_bf16 v[134:137], v[216:219], v[104:107], v[134:137]
	v_mfma_f32_16x16x32_bf16 v[138:141], v[220:223], v[104:107], v[138:141]
	v_mfma_f32_16x16x32_bf16 v[142:145], v[224:227], v[104:107], v[142:145]
	v_mfma_f32_16x16x32_bf16 v[146:149], v[228:231], v[104:107], v[146:149]
	v_div_scale_f32 v173, s[8:9], v172, v172, 1.0
	v_rcp_f32_e32 v175, v173
	s_nop 0
	v_fma_f32 v176, -v173, v175, 1.0
	v_fmac_f32_e32 v175, v176, v175
	v_div_scale_f32 v174, vcc, 1.0, v172, 1.0
	v_mul_f32_e32 v177, v174, v175
	v_fma_f32 v176, -v173, v177, v174
	v_fmac_f32_e32 v177, v176, v175
	v_fma_f32 v173, -v173, v177, v174
	v_div_fmas_f32 v173, v173, v175, v177
	v_div_fixup_f32 v180, v173, v172, 1.0
	v_lshlrev_b64 v[182:183], 11, v[116:117]
	v_lshl_add_u64 v[182:183], s[0:1], 0, v[182:183]
	v_lshl_add_u64 v[182:183], v[182:183], 0, s[36:37]
	v_lshl_add_u64 v[182:183], v[182:183], 0, v[2:3]
	v_mul_f32_e32 v134, v180, v134
	v_mul_f32_e32 v135, v180, v135
	v_mul_f32_e32 v136, v180, v136
	v_mul_f32_e32 v137, v180, v137
	v_cvt_pk_bf16_f32 v184, v134, v135
	v_cvt_pk_bf16_f32 v185, v136, v137
	s_nop 0
	global_store_dwordx2 v[182:183], v[184:185], off offset:1536
	v_mul_f32_e32 v138, v180, v138
	v_mul_f32_e32 v139, v180, v139
	v_mul_f32_e32 v140, v180, v140
	v_mul_f32_e32 v141, v180, v141
	v_cvt_pk_bf16_f32 v186, v138, v139
	v_cvt_pk_bf16_f32 v187, v140, v141
	s_nop 0
	global_store_dwordx2 v[182:183], v[186:187], off offset:1568
	v_mul_f32_e32 v142, v180, v142
	v_mul_f32_e32 v143, v180, v143
	v_mul_f32_e32 v144, v180, v144
	v_mul_f32_e32 v145, v180, v145
	v_cvt_pk_bf16_f32 v188, v142, v143
	v_cvt_pk_bf16_f32 v189, v144, v145
	s_nop 0
	global_store_dwordx2 v[182:183], v[188:189], off offset:1600
	v_mul_f32_e32 v146, v180, v146
	v_mul_f32_e32 v147, v180, v147
	v_mul_f32_e32 v148, v180, v148
	v_mul_f32_e32 v149, v180, v149
	v_cvt_pk_bf16_f32 v190, v146, v147
	v_cvt_pk_bf16_f32 v191, v148, v149
	s_nop 0
	global_store_dwordx2 v[182:183], v[190:191], off offset:1632
	ds_read_b128 v[200:203], v128
	ds_read_b128 v[204:207], v128 offset:64
	ds_read_b128 v[208:211], v128 offset:2304
	ds_read_b128 v[212:215], v128 offset:2368
	ds_read_b128 v[216:219], v128 offset:4608
	ds_read_b128 v[220:223], v128 offset:4672
	ds_read_b128 v[224:227], v128 offset:6912
	ds_read_b128 v[228:231], v128 offset:6976
	s_waitcnt vmcnt(12)
	s_waitcnt lgkmcnt(4)
	v_mfma_f32_16x16x32_bf16 v[44:47], v[200:203], v[40:43], 0
	v_mfma_f32_16x16x32_bf16 v[48:51], v[208:211], v[40:43], 0
	v_mfma_f32_16x16x32_bf16 v[44:47], v[204:207], v[36:39], v[44:47]
	v_mfma_f32_16x16x32_bf16 v[48:51], v[212:215], v[36:39], v[48:51]
	ds_read_b128 v[200:203], v128 offset:9216
	ds_read_b128 v[204:207], v128 offset:9280
	ds_read_b128 v[208:211], v128 offset:11520
	ds_read_b128 v[212:215], v128 offset:11584
	s_waitcnt lgkmcnt(4)
	v_mfma_f32_16x16x32_bf16 v[52:55], v[216:219], v[40:43], 0
	v_mfma_f32_16x16x32_bf16 v[56:59], v[224:227], v[40:43], 0
	v_mfma_f32_16x16x32_bf16 v[52:55], v[220:223], v[36:39], v[52:55]
	v_mfma_f32_16x16x32_bf16 v[56:59], v[228:231], v[36:39], v[56:59]
	ds_read_b128 v[216:219], v128 offset:13824
	ds_read_b128 v[220:223], v128 offset:13888
	ds_read_b128 v[224:227], v128 offset:16128
	ds_read_b128 v[228:231], v128 offset:16192
	s_waitcnt lgkmcnt(4)
	v_mfma_f32_16x16x32_bf16 v[64:67], v[200:203], v[40:43], 0
	v_mfma_f32_16x16x32_bf16 v[68:71], v[208:211], v[40:43], 0
	v_mfma_f32_16x16x32_bf16 v[64:67], v[204:207], v[36:39], v[64:67]
	v_mfma_f32_16x16x32_bf16 v[68:71], v[212:215], v[36:39], v[68:71]
	ds_read_b128 v[200:203], v128 offset:18432
	ds_read_b128 v[204:207], v128 offset:18496
	ds_read_b128 v[208:211], v128 offset:20736
	ds_read_b128 v[212:215], v128 offset:20800
	s_waitcnt lgkmcnt(4)
	v_mfma_f32_16x16x32_bf16 v[72:75], v[216:219], v[40:43], 0
	v_mfma_f32_16x16x32_bf16 v[76:79], v[224:227], v[40:43], 0
	v_mfma_f32_16x16x32_bf16 v[72:75], v[220:223], v[36:39], v[72:75]
	v_mfma_f32_16x16x32_bf16 v[76:79], v[228:231], v[36:39], v[76:79]
	ds_read_b128 v[216:219], v128 offset:23040
	ds_read_b128 v[220:223], v128 offset:23104
	ds_read_b128 v[224:227], v128 offset:25344
	ds_read_b128 v[228:231], v128 offset:25408
	s_waitcnt lgkmcnt(4)
	v_mfma_f32_16x16x32_bf16 v[80:83], v[200:203], v[40:43], 0
	v_mfma_f32_16x16x32_bf16 v[84:87], v[208:211], v[40:43], 0
	v_mfma_f32_16x16x32_bf16 v[80:83], v[204:207], v[36:39], v[80:83]
	v_mfma_f32_16x16x32_bf16 v[84:87], v[212:215], v[36:39], v[84:87]
	ds_read_b128 v[200:203], v128 offset:27648
	ds_read_b128 v[204:207], v128 offset:27712
	ds_read_b128 v[208:211], v128 offset:29952
	ds_read_b128 v[212:215], v128 offset:30016
	s_waitcnt lgkmcnt(4)
	v_mfma_f32_16x16x32_bf16 v[88:91], v[216:219], v[40:43], 0
	v_mfma_f32_16x16x32_bf16 v[92:95], v[224:227], v[40:43], 0
	v_mfma_f32_16x16x32_bf16 v[88:91], v[220:223], v[36:39], v[88:91]
	v_mfma_f32_16x16x32_bf16 v[92:95], v[228:231], v[36:39], v[92:95]
	ds_read_b128 v[216:219], v128 offset:32256
	ds_read_b128 v[220:223], v128 offset:32320
	ds_read_b128 v[224:227], v128 offset:34560
	ds_read_b128 v[228:231], v128 offset:34624
	s_waitcnt lgkmcnt(4)
	v_mfma_f32_16x16x32_bf16 v[96:99], v[200:203], v[40:43], 0
	v_mfma_f32_16x16x32_bf16 v[100:103], v[208:211], v[40:43], 0
	v_mfma_f32_16x16x32_bf16 v[96:99], v[204:207], v[36:39], v[96:99]
	v_mfma_f32_16x16x32_bf16 v[100:103], v[212:215], v[36:39], v[100:103]
	s_waitcnt lgkmcnt(0)
	v_mfma_f32_16x16x32_bf16 v[104:107], v[216:219], v[40:43], 0
	v_mfma_f32_16x16x32_bf16 v[130:133], v[224:227], v[40:43], 0
	v_mfma_f32_16x16x32_bf16 v[104:107], v[220:223], v[36:39], v[104:107]
	v_mfma_f32_16x16x32_bf16 v[130:133], v[228:231], v[36:39], v[130:133]
	s_nop 7
	v_max3_f32 v154, v44, v45, s13
	v_max3_f32 v154, v46, v47, v154
	v_max3_f32 v154, v48, v49, v154
	v_max3_f32 v154, v50, v51, v154
	v_max3_f32 v154, v52, v53, v154
	v_max3_f32 v154, v54, v55, v154
	v_max3_f32 v154, v56, v57, v154
	v_max3_f32 v154, v58, v59, v154
	v_max3_f32 v154, v64, v65, v154
	v_max3_f32 v154, v66, v67, v154
	v_max3_f32 v154, v68, v69, v154
	v_max3_f32 v154, v70, v71, v154
	v_max3_f32 v154, v72, v73, v154
	v_max3_f32 v154, v74, v75, v154
	v_max3_f32 v154, v76, v77, v154
	v_max3_f32 v154, v78, v79, v154
	v_max3_f32 v154, v80, v81, v154
	v_max3_f32 v154, v82, v83, v154
	v_max3_f32 v154, v84, v85, v154
	v_max3_f32 v154, v86, v87, v154
	v_max3_f32 v154, v88, v89, v154
	v_max3_f32 v154, v90, v91, v154
	v_max3_f32 v154, v92, v93, v154
	v_max3_f32 v154, v94, v95, v154
	v_max3_f32 v154, v96, v97, v154
	v_max3_f32 v154, v98, v99, v154
	v_max3_f32 v154, v100, v101, v154
	v_max3_f32 v154, v102, v103, v154
	v_max3_f32 v154, v104, v105, v154
	v_max3_f32 v154, v106, v107, v154
	v_max3_f32 v154, v130, v131, v154
	v_max3_f32 v154, v132, v133, v154
	v_mov_b32_e32 v155, v154
	s_nop 1
	v_permlane16_swap_b32_e32 v154, v155
	v_max_f32_e32 v154, v154, v155
	v_mov_b32_e32 v155, v154
	s_nop 1
	v_permlane32_swap_b32_e32 v154, v155
	v_max_f32_e32 v154, v154, v155
	v_sub_f32_e32 v44, v44, v154
	v_exp_f32_e32 v44, v44
	v_sub_f32_e32 v45, v45, v154
	v_exp_f32_e32 v45, v45
	v_add_f32_e32 v172, 0, v44
	v_sub_f32_e32 v46, v46, v154
	v_exp_f32_e32 v46, v46
	v_add_f32_e32 v172, v45, v172
	v_sub_f32_e32 v47, v47, v154
	v_exp_f32_e32 v47, v47
	v_add_f32_e32 v172, v46, v172
	v_sub_f32_e32 v48, v48, v154
	v_exp_f32_e32 v48, v48
	v_add_f32_e32 v172, v47, v172
	v_sub_f32_e32 v49, v49, v154
	v_exp_f32_e32 v49, v49
	v_add_f32_e32 v172, v48, v172
	v_sub_f32_e32 v50, v50, v154
	v_exp_f32_e32 v50, v50
	v_add_f32_e32 v172, v49, v172
	v_sub_f32_e32 v51, v51, v154
	v_exp_f32_e32 v51, v51
	v_add_f32_e32 v172, v50, v172
	v_sub_f32_e32 v52, v52, v154
	v_exp_f32_e32 v52, v52
	v_add_f32_e32 v172, v51, v172
	v_sub_f32_e32 v53, v53, v154
	v_exp_f32_e32 v53, v53
	v_add_f32_e32 v172, v52, v172
	v_sub_f32_e32 v54, v54, v154
	v_exp_f32_e32 v54, v54
	v_add_f32_e32 v172, v53, v172
	v_sub_f32_e32 v55, v55, v154
	v_exp_f32_e32 v55, v55
	v_add_f32_e32 v172, v54, v172
	v_sub_f32_e32 v56, v56, v154
	v_exp_f32_e32 v56, v56
	v_add_f32_e32 v172, v55, v172
	v_sub_f32_e32 v57, v57, v154
	v_exp_f32_e32 v57, v57
	v_add_f32_e32 v172, v56, v172
	v_sub_f32_e32 v58, v58, v154
	v_exp_f32_e32 v58, v58
	v_add_f32_e32 v172, v57, v172
	v_sub_f32_e32 v59, v59, v154
	v_exp_f32_e32 v59, v59
	v_add_f32_e32 v172, v58, v172
	v_sub_f32_e32 v64, v64, v154
	v_exp_f32_e32 v64, v64
	v_add_f32_e32 v172, v59, v172
	v_sub_f32_e32 v65, v65, v154
	v_exp_f32_e32 v65, v65
	v_add_f32_e32 v172, v64, v172
	v_sub_f32_e32 v66, v66, v154
	v_exp_f32_e32 v66, v66
	v_add_f32_e32 v172, v65, v172
	v_sub_f32_e32 v67, v67, v154
	v_exp_f32_e32 v67, v67
	v_add_f32_e32 v172, v66, v172
	v_sub_f32_e32 v68, v68, v154
	v_exp_f32_e32 v68, v68
	v_add_f32_e32 v172, v67, v172
	v_sub_f32_e32 v69, v69, v154
	v_exp_f32_e32 v69, v69
	v_add_f32_e32 v172, v68, v172
	v_sub_f32_e32 v70, v70, v154
	v_exp_f32_e32 v70, v70
	v_add_f32_e32 v172, v69, v172
	v_sub_f32_e32 v71, v71, v154
	v_exp_f32_e32 v71, v71
	v_add_f32_e32 v172, v70, v172
	v_sub_f32_e32 v72, v72, v154
	v_exp_f32_e32 v72, v72
	v_add_f32_e32 v172, v71, v172
	v_sub_f32_e32 v73, v73, v154
	v_exp_f32_e32 v73, v73
	v_add_f32_e32 v172, v72, v172
	v_sub_f32_e32 v74, v74, v154
	v_exp_f32_e32 v74, v74
	v_add_f32_e32 v172, v73, v172
	v_sub_f32_e32 v75, v75, v154
	v_exp_f32_e32 v75, v75
	v_add_f32_e32 v172, v74, v172
	v_sub_f32_e32 v76, v76, v154
	v_exp_f32_e32 v76, v76
	v_add_f32_e32 v172, v75, v172
	v_sub_f32_e32 v77, v77, v154
	v_exp_f32_e32 v77, v77
	v_add_f32_e32 v172, v76, v172
	v_sub_f32_e32 v78, v78, v154
	v_exp_f32_e32 v78, v78
	v_add_f32_e32 v172, v77, v172
	v_sub_f32_e32 v79, v79, v154
	v_exp_f32_e32 v79, v79
	v_add_f32_e32 v172, v78, v172
	v_sub_f32_e32 v80, v80, v154
	v_exp_f32_e32 v80, v80
	v_add_f32_e32 v172, v79, v172
	v_sub_f32_e32 v81, v81, v154
	v_exp_f32_e32 v81, v81
	v_add_f32_e32 v172, v80, v172
	v_sub_f32_e32 v82, v82, v154
	v_exp_f32_e32 v82, v82
	v_add_f32_e32 v172, v81, v172
	v_sub_f32_e32 v83, v83, v154
	v_exp_f32_e32 v83, v83
	v_add_f32_e32 v172, v82, v172
	v_sub_f32_e32 v84, v84, v154
	v_exp_f32_e32 v84, v84
	v_add_f32_e32 v172, v83, v172
	v_sub_f32_e32 v85, v85, v154
	v_exp_f32_e32 v85, v85
	v_add_f32_e32 v172, v84, v172
	v_sub_f32_e32 v86, v86, v154
	v_exp_f32_e32 v86, v86
	v_add_f32_e32 v172, v85, v172
	v_sub_f32_e32 v87, v87, v154
	v_exp_f32_e32 v87, v87
	v_add_f32_e32 v172, v86, v172
	v_sub_f32_e32 v88, v88, v154
	v_exp_f32_e32 v88, v88
	v_add_f32_e32 v172, v87, v172
	v_sub_f32_e32 v89, v89, v154
	v_exp_f32_e32 v89, v89
	v_add_f32_e32 v172, v88, v172
	v_sub_f32_e32 v90, v90, v154
	v_exp_f32_e32 v90, v90
	v_add_f32_e32 v172, v89, v172
	v_sub_f32_e32 v91, v91, v154
	v_exp_f32_e32 v91, v91
	v_add_f32_e32 v172, v90, v172
	v_sub_f32_e32 v92, v92, v154
	v_exp_f32_e32 v92, v92
	v_add_f32_e32 v172, v91, v172
	v_sub_f32_e32 v93, v93, v154
	v_exp_f32_e32 v93, v93
	v_add_f32_e32 v172, v92, v172
	v_sub_f32_e32 v94, v94, v154
	v_exp_f32_e32 v94, v94
	v_add_f32_e32 v172, v93, v172
	v_sub_f32_e32 v95, v95, v154
	v_exp_f32_e32 v95, v95
	v_add_f32_e32 v172, v94, v172
	v_sub_f32_e32 v96, v96, v154
	v_exp_f32_e32 v96, v96
	v_add_f32_e32 v172, v95, v172
	v_sub_f32_e32 v97, v97, v154
	v_exp_f32_e32 v97, v97
	v_add_f32_e32 v172, v96, v172
	v_sub_f32_e32 v98, v98, v154
	v_exp_f32_e32 v98, v98
	v_add_f32_e32 v172, v97, v172
	v_sub_f32_e32 v99, v99, v154
	v_exp_f32_e32 v99, v99
	v_add_f32_e32 v172, v98, v172
	v_sub_f32_e32 v100, v100, v154
	v_exp_f32_e32 v100, v100
	v_add_f32_e32 v172, v99, v172
	v_sub_f32_e32 v101, v101, v154
	v_exp_f32_e32 v101, v101
	v_add_f32_e32 v172, v100, v172
	v_sub_f32_e32 v102, v102, v154
	v_exp_f32_e32 v102, v102
	v_add_f32_e32 v172, v101, v172
	v_sub_f32_e32 v103, v103, v154
	v_exp_f32_e32 v103, v103
	v_add_f32_e32 v172, v102, v172
	v_sub_f32_e32 v104, v104, v154
	v_exp_f32_e32 v104, v104
	v_add_f32_e32 v172, v103, v172
	v_sub_f32_e32 v105, v105, v154
	v_exp_f32_e32 v105, v105
	v_add_f32_e32 v172, v104, v172
	v_sub_f32_e32 v106, v106, v154
	v_exp_f32_e32 v106, v106
	v_add_f32_e32 v172, v105, v172
	v_sub_f32_e32 v107, v107, v154
	v_exp_f32_e32 v107, v107
	v_add_f32_e32 v172, v106, v172
	v_sub_f32_e32 v130, v130, v154
	v_exp_f32_e32 v130, v130
	v_add_f32_e32 v172, v107, v172
	v_sub_f32_e32 v131, v131, v154
	v_exp_f32_e32 v131, v131
	v_add_f32_e32 v172, v130, v172
	v_sub_f32_e32 v132, v132, v154
	v_exp_f32_e32 v132, v132
	v_add_f32_e32 v172, v131, v172
	v_sub_f32_e32 v133, v133, v154
	v_exp_f32_e32 v133, v133
	v_add_f32_e32 v172, v132, v172
	s_nop 0
	v_add_f32_e32 v172, v133, v172
	ds_read2_b64 v[200:203], v150 offset0:0 offset1:4
	ds_read2_b64 v[204:207], v151 offset0:0 offset1:4
	ds_read2_b64 v[208:211], v152 offset0:0 offset1:4
	ds_read2_b64 v[212:215], v153 offset0:0 offset1:4
	ds_read2_b64 v[216:219], v150 offset0:8 offset1:12
	ds_read2_b64 v[220:223], v151 offset0:8 offset1:12
	ds_read2_b64 v[224:227], v152 offset0:8 offset1:12
	ds_read2_b64 v[228:231], v153 offset0:8 offset1:12
	v_mov_b32_e32 v155, v172
	s_nop 1
	v_permlane16_swap_b32_e32 v172, v155
	v_add_f32_e32 v172, v172, v155
	v_mov_b32_e32 v155, v172
	s_nop 1
	v_permlane32_swap_b32_e32 v172, v155
	v_add_f32_e32 v172, v172, v155
	v_cvt_pk_bf16_f32 v44, v44, v45
	v_cvt_pk_bf16_f32 v45, v46, v47
	v_cvt_pk_bf16_f32 v46, v48, v49
	v_cvt_pk_bf16_f32 v47, v50, v51
	v_cvt_pk_bf16_f32 v52, v52, v53
	v_cvt_pk_bf16_f32 v53, v54, v55
	v_cvt_pk_bf16_f32 v54, v56, v57
	v_cvt_pk_bf16_f32 v55, v58, v59
	s_waitcnt lgkmcnt(4)
	s_nop 1
	v_mfma_f32_16x16x32_bf16 v[134:137], v[200:203], v[44:47], 0
	v_mfma_f32_16x16x32_bf16 v[138:141], v[204:207], v[44:47], 0
	v_mfma_f32_16x16x32_bf16 v[142:145], v[208:211], v[44:47], 0
	v_mfma_f32_16x16x32_bf16 v[146:149], v[212:215], v[44:47], 0
	ds_read2_b64 v[200:203], v150 offset0:16 offset1:20
	ds_read2_b64 v[204:207], v151 offset0:16 offset1:20
	ds_read2_b64 v[208:211], v152 offset0:16 offset1:20
	ds_read2_b64 v[212:215], v153 offset0:16 offset1:20
	v_cvt_pk_bf16_f32 v64, v64, v65
	v_cvt_pk_bf16_f32 v65, v66, v67
	v_cvt_pk_bf16_f32 v66, v68, v69
	v_cvt_pk_bf16_f32 v67, v70, v71
	s_waitcnt lgkmcnt(4)
	s_nop 1
	v_mfma_f32_16x16x32_bf16 v[134:137], v[216:219], v[52:55], v[134:137]
	v_mfma_f32_16x16x32_bf16 v[138:141], v[220:223], v[52:55], v[138:141]
	v_mfma_f32_16x16x32_bf16 v[142:145], v[224:227], v[52:55], v[142:145]
	v_mfma_f32_16x16x32_bf16 v[146:149], v[228:231], v[52:55], v[146:149]
	ds_read2_b64 v[216:219], v150 offset0:24 offset1:28
	ds_read2_b64 v[220:223], v151 offset0:24 offset1:28
	ds_read2_b64 v[224:227], v152 offset0:24 offset1:28
	ds_read2_b64 v[228:231], v153 offset0:24 offset1:28
	v_cvt_pk_bf16_f32 v72, v72, v73
	v_cvt_pk_bf16_f32 v73, v74, v75
	v_cvt_pk_bf16_f32 v74, v76, v77
	v_cvt_pk_bf16_f32 v75, v78, v79
	s_waitcnt lgkmcnt(4)
	s_nop 1
	v_mfma_f32_16x16x32_bf16 v[134:137], v[200:203], v[64:67], v[134:137]
	v_mfma_f32_16x16x32_bf16 v[138:141], v[204:207], v[64:67], v[138:141]
	v_mfma_f32_16x16x32_bf16 v[142:145], v[208:211], v[64:67], v[142:145]
	v_mfma_f32_16x16x32_bf16 v[146:149], v[212:215], v[64:67], v[146:149]
	ds_read2_b64 v[200:203], v150 offset0:32 offset1:36
	ds_read2_b64 v[204:207], v151 offset0:32 offset1:36
	ds_read2_b64 v[208:211], v152 offset0:32 offset1:36
	ds_read2_b64 v[212:215], v153 offset0:32 offset1:36
	v_cvt_pk_bf16_f32 v80, v80, v81
	v_cvt_pk_bf16_f32 v81, v82, v83
	v_cvt_pk_bf16_f32 v82, v84, v85
	v_cvt_pk_bf16_f32 v83, v86, v87
	s_waitcnt lgkmcnt(4)
	s_nop 1
	v_mfma_f32_16x16x32_bf16 v[134:137], v[216:219], v[72:75], v[134:137]
	v_mfma_f32_16x16x32_bf16 v[138:141], v[220:223], v[72:75], v[138:141]
	v_mfma_f32_16x16x32_bf16 v[142:145], v[224:227], v[72:75], v[142:145]
	v_mfma_f32_16x16x32_bf16 v[146:149], v[228:231], v[72:75], v[146:149]
	ds_read2_b64 v[216:219], v150 offset0:40 offset1:44
	ds_read2_b64 v[220:223], v151 offset0:40 offset1:44
	ds_read2_b64 v[224:227], v152 offset0:40 offset1:44
	ds_read2_b64 v[228:231], v153 offset0:40 offset1:44
	v_cvt_pk_bf16_f32 v88, v88, v89
	v_cvt_pk_bf16_f32 v89, v90, v91
	v_cvt_pk_bf16_f32 v90, v92, v93
	v_cvt_pk_bf16_f32 v91, v94, v95
	s_waitcnt lgkmcnt(4)
	s_nop 1
	v_mfma_f32_16x16x32_bf16 v[134:137], v[200:203], v[80:83], v[134:137]
	v_mfma_f32_16x16x32_bf16 v[138:141], v[204:207], v[80:83], v[138:141]
	v_mfma_f32_16x16x32_bf16 v[142:145], v[208:211], v[80:83], v[142:145]
	v_mfma_f32_16x16x32_bf16 v[146:149], v[212:215], v[80:83], v[146:149]
	ds_read2_b64 v[200:203], v150 offset0:48 offset1:52
	ds_read2_b64 v[204:207], v151 offset0:48 offset1:52
	ds_read2_b64 v[208:211], v152 offset0:48 offset1:52
	ds_read2_b64 v[212:215], v153 offset0:48 offset1:52
	v_cvt_pk_bf16_f32 v96, v96, v97
	v_cvt_pk_bf16_f32 v97, v98, v99
	v_cvt_pk_bf16_f32 v98, v100, v101
	v_cvt_pk_bf16_f32 v99, v102, v103
	s_waitcnt lgkmcnt(4)
	s_nop 1
	v_mfma_f32_16x16x32_bf16 v[134:137], v[216:219], v[88:91], v[134:137]
	v_mfma_f32_16x16x32_bf16 v[138:141], v[220:223], v[88:91], v[138:141]
	v_mfma_f32_16x16x32_bf16 v[142:145], v[224:227], v[88:91], v[142:145]
	v_mfma_f32_16x16x32_bf16 v[146:149], v[228:231], v[88:91], v[146:149]
	ds_read2_b64 v[216:219], v150 offset0:56 offset1:60
	ds_read2_b64 v[220:223], v151 offset0:56 offset1:60
	ds_read2_b64 v[224:227], v152 offset0:56 offset1:60
	ds_read2_b64 v[228:231], v153 offset0:56 offset1:60
	v_cvt_pk_bf16_f32 v104, v104, v105
	v_cvt_pk_bf16_f32 v105, v106, v107
	v_cvt_pk_bf16_f32 v106, v130, v131
	v_cvt_pk_bf16_f32 v107, v132, v133
	s_waitcnt lgkmcnt(4)
	s_nop 1
	v_mfma_f32_16x16x32_bf16 v[134:137], v[200:203], v[96:99], v[134:137]
	v_mfma_f32_16x16x32_bf16 v[138:141], v[204:207], v[96:99], v[138:141]
	v_mfma_f32_16x16x32_bf16 v[142:145], v[208:211], v[96:99], v[142:145]
	v_mfma_f32_16x16x32_bf16 v[146:149], v[212:215], v[96:99], v[146:149]
	s_waitcnt lgkmcnt(0)
	s_nop 1
	v_mfma_f32_16x16x32_bf16 v[134:137], v[216:219], v[104:107], v[134:137]
	v_mfma_f32_16x16x32_bf16 v[138:141], v[220:223], v[104:107], v[138:141]
	v_mfma_f32_16x16x32_bf16 v[142:145], v[224:227], v[104:107], v[142:145]
	v_mfma_f32_16x16x32_bf16 v[146:149], v[228:231], v[104:107], v[146:149]
	v_div_scale_f32 v173, s[8:9], v172, v172, 1.0
	v_rcp_f32_e32 v175, v173
	s_nop 0
	v_fma_f32 v176, -v173, v175, 1.0
	v_fmac_f32_e32 v175, v176, v175
	v_div_scale_f32 v174, vcc, 1.0, v172, 1.0
	v_mul_f32_e32 v177, v174, v175
	v_fma_f32 v176, -v173, v177, v174
	v_fmac_f32_e32 v177, v176, v175
	v_fma_f32 v173, -v173, v177, v174
	v_div_fmas_f32 v173, v173, v175, v177
	v_div_fixup_f32 v180, v173, v172, 1.0
	v_lshlrev_b64 v[182:183], 11, v[114:115]
	v_lshl_add_u64 v[182:183], s[0:1], 0, v[182:183]
	v_lshl_add_u64 v[182:183], v[182:183], 0, s[36:37]
	v_lshl_add_u64 v[182:183], v[182:183], 0, v[2:3]
	v_mul_f32_e32 v134, v180, v134
	v_mul_f32_e32 v135, v180, v135
	v_mul_f32_e32 v136, v180, v136
	v_mul_f32_e32 v137, v180, v137
	v_cvt_pk_bf16_f32 v184, v134, v135
	v_cvt_pk_bf16_f32 v185, v136, v137
	s_nop 0
	global_store_dwordx2 v[182:183], v[184:185], off offset:1536
	v_mul_f32_e32 v138, v180, v138
	v_mul_f32_e32 v139, v180, v139
	v_mul_f32_e32 v140, v180, v140
	v_mul_f32_e32 v141, v180, v141
	v_cvt_pk_bf16_f32 v186, v138, v139
	v_cvt_pk_bf16_f32 v187, v140, v141
	s_nop 0
	global_store_dwordx2 v[182:183], v[186:187], off offset:1568
	v_mul_f32_e32 v142, v180, v142
	v_mul_f32_e32 v143, v180, v143
	v_mul_f32_e32 v144, v180, v144
	v_mul_f32_e32 v145, v180, v145
	v_cvt_pk_bf16_f32 v188, v142, v143
	v_cvt_pk_bf16_f32 v189, v144, v145
	s_nop 0
	global_store_dwordx2 v[182:183], v[188:189], off offset:1600
	v_mul_f32_e32 v146, v180, v146
	v_mul_f32_e32 v147, v180, v147
	v_mul_f32_e32 v148, v180, v148
	v_mul_f32_e32 v149, v180, v149
	v_cvt_pk_bf16_f32 v190, v146, v147
	v_cvt_pk_bf16_f32 v191, v148, v149
	s_nop 0
	global_store_dwordx2 v[182:183], v[190:191], off offset:1632
	s_mov_b32 s13, s12
	s_andn2_b64 vcc, exec, s[6:7]
	s_barrier
	s_cbranch_vccz .LBB0_582
